# W_out GEMM epilogue hand-scheduled: residual loads of four row sets in flight and re-issued as consumed, batched cross-lane reductions
# baseline (speedup 1.0000x reference)
.LBB0_170:
	s_add_u32 s20, s48, 0xfffc0080
	s_addc_u32 s21, s49, -1
	s_add_i32 s60, 0, 0x10000
	v_add_u32_e32 v140, s60, v232
	ds_read_b128 v[128:131], v140
	ds_read_b128 v[132:135], v140 offset:1024
	ds_read_b128 v[136:139], v140 offset:2048
	ds_read_b128 v[140:143], v140 offset:3072
	s_cmp_eq_u32 s57, 12
	s_cselect_b32 s51, s43, s21
	s_cselect_b32 s50, s24, s20
	s_cselect_b32 s29, s1, vcc_hi
	s_cselect_b32 s28, s25, vcc_lo
	s_add_i32 m0, s55, 0xc000
	ds_read_b128 v[144:147], v234
	ds_read_b128 v[148:151], v234 offset:1024
	ds_read_b128 v[152:155], v234 offset:2048
	ds_read_b128 v[156:159], v234 offset:3072
	ds_read_b128 v[160:163], v234 offset:4096
	ds_read_b128 v[164:167], v234 offset:5120
	ds_read_b128 v[168:171], v234 offset:6144
	ds_read_b128 v[172:175], v234 offset:7168
	global_load_lds_dwordx4 v204, s[48:49]
	s_add_i32 m0, s55, 0xe000
	s_nop 0
	global_load_lds_dwordx4 v206, s[48:49]
	s_waitcnt lgkmcnt(8)
	s_barrier
	s_waitcnt lgkmcnt(0)
	v_mfma_f32_16x16x32_bf16 v[124:127], v[128:131], v[144:147], v[124:127]
	v_mfma_f32_16x16x32_bf16 v[120:123], v[136:139], v[144:147], v[120:123]
	v_mfma_f32_16x16x32_bf16 v[108:111], v[128:131], v[152:155], v[108:111]
	v_mfma_f32_16x16x32_bf16 v[104:107], v[136:139], v[152:155], v[104:107]
	v_mfma_f32_16x16x32_bf16 v[92:95], v[128:131], v[160:163], v[92:95]
	v_mfma_f32_16x16x32_bf16 v[88:91], v[136:139], v[160:163], v[88:91]
	v_mfma_f32_16x16x32_bf16 v[76:79], v[128:131], v[168:171], v[76:79]
	v_mfma_f32_16x16x32_bf16 v[72:75], v[136:139], v[168:171], v[72:75]
	v_mfma_f32_16x16x32_bf16 v[124:127], v[132:135], v[148:151], v[124:127]
	v_mfma_f32_16x16x32_bf16 v[120:123], v[140:143], v[148:151], v[120:123]
	v_mfma_f32_16x16x32_bf16 v[108:111], v[132:135], v[156:159], v[108:111]
	v_mfma_f32_16x16x32_bf16 v[104:107], v[140:143], v[156:159], v[104:107]
	v_mfma_f32_16x16x32_bf16 v[92:95], v[132:135], v[164:167], v[92:95]
	v_mfma_f32_16x16x32_bf16 v[88:91], v[140:143], v[164:167], v[88:91]
	v_mfma_f32_16x16x32_bf16 v[76:79], v[132:135], v[172:175], v[76:79]
	v_mfma_f32_16x16x32_bf16 v[72:75], v[140:143], v[172:175], v[72:75]
	s_barrier
	s_add_i32 s61, 0, 0x14000
	v_add_u32_e32 v184, s61, v232
	s_add_i32 s20, s60, s54
	ds_read_b128 v[208:211], v184
	ds_read_b128 v[212:215], v184 offset:1024
	ds_read_b128 v[216:219], v184 offset:2048
	ds_read_b128 v[236:239], v184 offset:3072
	s_add_u32 s72, s28, s52
	s_addc_u32 s73, s29, s53
	s_mov_b32 m0, s20
	s_nop 0
	global_load_lds_dwordx4 v176, s[28:29]
	s_add_i32 m0, s20, 0x2000
	s_nop 0
	global_load_lds_dwordx4 v198, s[28:29]
	s_barrier
	s_waitcnt lgkmcnt(0)
	v_mfma_f32_16x16x32_bf16 v[116:119], v[208:211], v[144:147], v[116:119]
	v_mfma_f32_16x16x32_bf16 v[112:115], v[216:219], v[144:147], v[112:115]
	v_mfma_f32_16x16x32_bf16 v[100:103], v[208:211], v[152:155], v[100:103]
	v_mfma_f32_16x16x32_bf16 v[96:99], v[216:219], v[152:155], v[96:99]
	v_mfma_f32_16x16x32_bf16 v[84:87], v[208:211], v[160:163], v[84:87]
	v_mfma_f32_16x16x32_bf16 v[80:83], v[216:219], v[160:163], v[80:83]
	v_mfma_f32_16x16x32_bf16 v[68:71], v[208:211], v[168:171], v[68:71]
	v_mfma_f32_16x16x32_bf16 v[64:67], v[216:219], v[168:171], v[64:67]
	v_mfma_f32_16x16x32_bf16 v[116:119], v[212:215], v[148:151], v[116:119]
	v_mfma_f32_16x16x32_bf16 v[112:115], v[236:239], v[148:151], v[112:115]
	v_mfma_f32_16x16x32_bf16 v[100:103], v[212:215], v[156:159], v[100:103]
	v_mfma_f32_16x16x32_bf16 v[96:99], v[236:239], v[156:159], v[96:99]
	v_mfma_f32_16x16x32_bf16 v[84:87], v[212:215], v[164:167], v[84:87]
	v_mfma_f32_16x16x32_bf16 v[80:83], v[236:239], v[164:167], v[80:83]
	v_mfma_f32_16x16x32_bf16 v[68:71], v[212:215], v[172:175], v[68:71]
	v_mfma_f32_16x16x32_bf16 v[64:67], v[236:239], v[172:175], v[64:67]
	s_mov_b32 m0, s55
	s_add_u32 s70, s50, s52
	s_addc_u32 s71, s51, s53
	s_barrier
	ds_read_b128 v[144:147], v234 offset:16384
	ds_read_b128 v[148:151], v234 offset:17408
	ds_read_b128 v[152:155], v234 offset:18432
	ds_read_b128 v[156:159], v234 offset:19456
	ds_read_b128 v[160:163], v234 offset:20480
	ds_read_b128 v[164:167], v234 offset:21504
	ds_read_b128 v[168:171], v234 offset:22528
	ds_read_b128 v[172:175], v234 offset:23552
	global_load_lds_dwordx4 v202, s[50:51]
	s_mov_b32 m0, s56
	s_nop 0
	global_load_lds_dwordx4 v200, s[50:51]
	s_barrier
	s_waitcnt lgkmcnt(0)
	v_mfma_f32_16x16x32_bf16 v[60:63], v[128:131], v[144:147], v[60:63]
	v_mfma_f32_16x16x32_bf16 v[56:59], v[136:139], v[144:147], v[56:59]
	v_mfma_f32_16x16x32_bf16 v[44:47], v[128:131], v[152:155], v[44:47]
	v_mfma_f32_16x16x32_bf16 v[40:43], v[136:139], v[152:155], v[40:43]
	v_mfma_f32_16x16x32_bf16 v[28:31], v[128:131], v[160:163], v[28:31]
	v_mfma_f32_16x16x32_bf16 v[24:27], v[136:139], v[160:163], v[24:27]
	v_mfma_f32_16x16x32_bf16 v[12:15], v[128:131], v[168:171], v[12:15]
	v_mfma_f32_16x16x32_bf16 v[8:11], v[136:139], v[168:171], v[8:11]
	v_mfma_f32_16x16x32_bf16 v[60:63], v[132:135], v[148:151], v[60:63]
	v_mfma_f32_16x16x32_bf16 v[56:59], v[140:143], v[148:151], v[56:59]
	v_mfma_f32_16x16x32_bf16 v[44:47], v[132:135], v[156:159], v[44:47]
	v_mfma_f32_16x16x32_bf16 v[40:43], v[140:143], v[156:159], v[40:43]
	v_mfma_f32_16x16x32_bf16 v[28:31], v[132:135], v[164:167], v[28:31]
	v_mfma_f32_16x16x32_bf16 v[24:27], v[140:143], v[164:167], v[24:27]
	v_mfma_f32_16x16x32_bf16 v[12:15], v[132:135], v[172:175], v[12:15]
	v_mfma_f32_16x16x32_bf16 v[8:11], v[140:143], v[172:175], v[8:11]
	s_barrier
	s_add_u32 s20, s28, 0x40000
	s_addc_u32 s21, s29, 0
	s_add_i32 s60, s61, s54
	s_mov_b32 m0, s60
	s_nop 0
	global_load_lds_dwordx4 v176, s[20:21]
	s_add_i32 m0, s60, 0x2000
	s_nop 0
	global_load_lds_dwordx4 v198, s[20:21]
	s_waitcnt vmcnt(6)
	s_barrier
	v_mfma_f32_16x16x32_bf16 v[52:55], v[208:211], v[144:147], v[52:55]
	v_mfma_f32_16x16x32_bf16 v[48:51], v[216:219], v[144:147], v[48:51]
	v_mfma_f32_16x16x32_bf16 v[36:39], v[208:211], v[152:155], v[36:39]
	v_mfma_f32_16x16x32_bf16 v[32:35], v[216:219], v[152:155], v[32:35]
	v_mfma_f32_16x16x32_bf16 v[20:23], v[208:211], v[160:163], v[20:23]
	v_mfma_f32_16x16x32_bf16 v[16:19], v[216:219], v[160:163], v[16:19]
	v_mfma_f32_16x16x32_bf16 v[4:7], v[208:211], v[168:171], v[4:7]
	v_mfma_f32_16x16x32_bf16 v[0:3], v[216:219], v[168:171], v[0:3]
	v_mfma_f32_16x16x32_bf16 v[52:55], v[212:215], v[148:151], v[52:55]
	v_mfma_f32_16x16x32_bf16 v[48:51], v[236:239], v[148:151], v[48:51]
	v_mfma_f32_16x16x32_bf16 v[36:39], v[212:215], v[156:159], v[36:39]
	v_mfma_f32_16x16x32_bf16 v[32:35], v[236:239], v[156:159], v[32:35]
	v_mfma_f32_16x16x32_bf16 v[20:23], v[212:215], v[164:167], v[20:23]
	v_mfma_f32_16x16x32_bf16 v[16:19], v[236:239], v[164:167], v[16:19]
	v_mfma_f32_16x16x32_bf16 v[4:7], v[212:215], v[172:175], v[4:7]
	v_mfma_f32_16x16x32_bf16 v[0:3], v[236:239], v[172:175], v[0:3]
	s_add_i32 s60, 0, 0x18000
	v_add_u32_e32 v140, s60, v232
	s_barrier
	ds_read_b128 v[128:131], v140
	ds_read_b128 v[132:135], v140 offset:1024
	ds_read_b128 v[136:139], v140 offset:2048
	ds_read_b128 v[140:143], v140 offset:3072
	s_add_u32 s20, s50, 0x40000
	s_addc_u32 s21, s51, 0
	s_mov_b32 m0, s7
	ds_read_b128 v[144:147], v234 offset:32768
	ds_read_b128 v[148:151], v234 offset:33792
	ds_read_b128 v[152:155], v234 offset:34816
	ds_read_b128 v[156:159], v234 offset:35840
	ds_read_b128 v[160:163], v234 offset:36864
	ds_read_b128 v[164:167], v234 offset:37888
	ds_read_b128 v[168:171], v234 offset:38912
	ds_read_b128 v[172:175], v234 offset:39936
	global_load_lds_dwordx4 v202, s[20:21]
	s_mov_b32 m0, s15
	s_nop 0
	global_load_lds_dwordx4 v200, s[20:21]
	s_waitcnt lgkmcnt(8)
	s_barrier
	s_waitcnt lgkmcnt(0)
	v_mfma_f32_16x16x32_bf16 v[124:127], v[128:131], v[144:147], v[124:127]
	v_mfma_f32_16x16x32_bf16 v[120:123], v[136:139], v[144:147], v[120:123]
	v_mfma_f32_16x16x32_bf16 v[108:111], v[128:131], v[152:155], v[108:111]
	v_mfma_f32_16x16x32_bf16 v[104:107], v[136:139], v[152:155], v[104:107]
	v_mfma_f32_16x16x32_bf16 v[92:95], v[128:131], v[160:163], v[92:95]
	v_mfma_f32_16x16x32_bf16 v[88:91], v[136:139], v[160:163], v[88:91]
	v_mfma_f32_16x16x32_bf16 v[76:79], v[128:131], v[168:171], v[76:79]
	v_mfma_f32_16x16x32_bf16 v[72:75], v[136:139], v[168:171], v[72:75]
	v_mfma_f32_16x16x32_bf16 v[124:127], v[132:135], v[148:151], v[124:127]
	v_mfma_f32_16x16x32_bf16 v[120:123], v[140:143], v[148:151], v[120:123]
	v_mfma_f32_16x16x32_bf16 v[108:111], v[132:135], v[156:159], v[108:111]
	v_mfma_f32_16x16x32_bf16 v[104:107], v[140:143], v[156:159], v[104:107]
	v_mfma_f32_16x16x32_bf16 v[92:95], v[132:135], v[164:167], v[92:95]
	v_mfma_f32_16x16x32_bf16 v[88:91], v[140:143], v[164:167], v[88:91]
	v_mfma_f32_16x16x32_bf16 v[76:79], v[132:135], v[172:175], v[76:79]
	v_mfma_f32_16x16x32_bf16 v[72:75], v[140:143], v[172:175], v[72:75]
	s_barrier
	s_add_i32 s50, 0, 0x1c000
	s_add_i32 s20, s60, s54
	v_add_u32_e32 v235, s50, v232
	s_mov_b32 m0, s20
	ds_read_b128 v[208:211], v235
	ds_read_b128 v[212:215], v235 offset:1024
	ds_read_b128 v[216:219], v235 offset:2048
	ds_read_b128 v[236:239], v235 offset:3072
	global_load_lds_dwordx4 v176, s[72:73]
	s_add_i32 m0, s20, 0x2000
	s_nop 0
	global_load_lds_dwordx4 v198, s[72:73]
	s_barrier
	s_waitcnt lgkmcnt(0)
	v_mfma_f32_16x16x32_bf16 v[116:119], v[208:211], v[144:147], v[116:119]
	v_mfma_f32_16x16x32_bf16 v[112:115], v[216:219], v[144:147], v[112:115]
	v_mfma_f32_16x16x32_bf16 v[100:103], v[208:211], v[152:155], v[100:103]
	v_mfma_f32_16x16x32_bf16 v[96:99], v[216:219], v[152:155], v[96:99]
	v_mfma_f32_16x16x32_bf16 v[84:87], v[208:211], v[160:163], v[84:87]
	v_mfma_f32_16x16x32_bf16 v[80:83], v[216:219], v[160:163], v[80:83]
	v_mfma_f32_16x16x32_bf16 v[68:71], v[208:211], v[168:171], v[68:71]
	v_mfma_f32_16x16x32_bf16 v[64:67], v[216:219], v[168:171], v[64:67]
	v_mfma_f32_16x16x32_bf16 v[116:119], v[212:215], v[148:151], v[116:119]
	v_mfma_f32_16x16x32_bf16 v[112:115], v[236:239], v[148:151], v[112:115]
	v_mfma_f32_16x16x32_bf16 v[100:103], v[212:215], v[156:159], v[100:103]
	v_mfma_f32_16x16x32_bf16 v[96:99], v[236:239], v[156:159], v[96:99]
	v_mfma_f32_16x16x32_bf16 v[84:87], v[212:215], v[164:167], v[84:87]
	v_mfma_f32_16x16x32_bf16 v[80:83], v[236:239], v[164:167], v[80:83]
	v_mfma_f32_16x16x32_bf16 v[68:71], v[212:215], v[172:175], v[68:71]
	v_mfma_f32_16x16x32_bf16 v[64:67], v[236:239], v[172:175], v[64:67]
	s_mov_b32 m0, s3
	s_barrier
	ds_read_b128 v[144:147], v234 offset:49152
	ds_read_b128 v[148:151], v234 offset:50176
	ds_read_b128 v[152:155], v234 offset:51200
	ds_read_b128 v[156:159], v234 offset:52224
	ds_read_b128 v[160:163], v234 offset:53248
	ds_read_b128 v[164:167], v234 offset:54272
	ds_read_b128 v[168:171], v234 offset:55296
	ds_read_b128 v[172:175], v234 offset:56320
	global_load_lds_dwordx4 v202, s[70:71]
	s_mov_b32 m0, s6
	s_nop 0
	global_load_lds_dwordx4 v200, s[70:71]
	s_barrier
	s_waitcnt lgkmcnt(0)
	v_mfma_f32_16x16x32_bf16 v[60:63], v[128:131], v[144:147], v[60:63]
	v_mfma_f32_16x16x32_bf16 v[56:59], v[136:139], v[144:147], v[56:59]
	v_mfma_f32_16x16x32_bf16 v[44:47], v[128:131], v[152:155], v[44:47]
	v_mfma_f32_16x16x32_bf16 v[40:43], v[136:139], v[152:155], v[40:43]
	v_mfma_f32_16x16x32_bf16 v[28:31], v[128:131], v[160:163], v[28:31]
	v_mfma_f32_16x16x32_bf16 v[24:27], v[136:139], v[160:163], v[24:27]
	v_mfma_f32_16x16x32_bf16 v[12:15], v[128:131], v[168:171], v[12:15]
	v_mfma_f32_16x16x32_bf16 v[8:11], v[136:139], v[168:171], v[8:11]
	v_mfma_f32_16x16x32_bf16 v[60:63], v[132:135], v[148:151], v[60:63]
	v_mfma_f32_16x16x32_bf16 v[56:59], v[140:143], v[148:151], v[56:59]
	v_mfma_f32_16x16x32_bf16 v[44:47], v[132:135], v[156:159], v[44:47]
	v_mfma_f32_16x16x32_bf16 v[40:43], v[140:143], v[156:159], v[40:43]
	v_mfma_f32_16x16x32_bf16 v[28:31], v[132:135], v[164:167], v[28:31]
	v_mfma_f32_16x16x32_bf16 v[24:27], v[140:143], v[164:167], v[24:27]
	v_mfma_f32_16x16x32_bf16 v[12:15], v[132:135], v[172:175], v[12:15]
	v_mfma_f32_16x16x32_bf16 v[8:11], v[140:143], v[172:175], v[8:11]
	s_barrier
	s_add_u32 s20, s28, 0x40080
	s_addc_u32 s21, s29, 0
	s_add_i32 s28, s50, s54
	s_mov_b32 m0, s28
	s_nop 0
	global_load_lds_dwordx4 v176, s[20:21]
	s_add_i32 m0, s28, 0x2000
	s_nop 0
	global_load_lds_dwordx4 v198, s[20:21]
	s_waitcnt vmcnt(6)
	s_barrier
	v_mfma_f32_16x16x32_bf16 v[52:55], v[208:211], v[144:147], v[52:55]
	v_mfma_f32_16x16x32_bf16 v[48:51], v[216:219], v[144:147], v[48:51]
	v_mfma_f32_16x16x32_bf16 v[36:39], v[208:211], v[152:155], v[36:39]
	v_mfma_f32_16x16x32_bf16 v[32:35], v[216:219], v[152:155], v[32:35]
	v_mfma_f32_16x16x32_bf16 v[20:23], v[208:211], v[160:163], v[20:23]
	v_mfma_f32_16x16x32_bf16 v[16:19], v[216:219], v[160:163], v[16:19]
	v_mfma_f32_16x16x32_bf16 v[4:7], v[208:211], v[168:171], v[4:7]
	v_mfma_f32_16x16x32_bf16 v[0:3], v[216:219], v[168:171], v[0:3]
	v_mfma_f32_16x16x32_bf16 v[52:55], v[212:215], v[148:151], v[52:55]
	v_mfma_f32_16x16x32_bf16 v[48:51], v[236:239], v[148:151], v[48:51]
	v_mfma_f32_16x16x32_bf16 v[36:39], v[212:215], v[156:159], v[36:39]
	v_mfma_f32_16x16x32_bf16 v[32:35], v[236:239], v[156:159], v[32:35]
	v_mfma_f32_16x16x32_bf16 v[20:23], v[212:215], v[164:167], v[20:23]
	v_mfma_f32_16x16x32_bf16 v[16:19], v[236:239], v[164:167], v[16:19]
	v_mfma_f32_16x16x32_bf16 v[4:7], v[212:215], v[172:175], v[4:7]
	v_mfma_f32_16x16x32_bf16 v[0:3], v[236:239], v[172:175], v[0:3]
	s_add_i32 s57, s57, 2
	s_add_u32 s48, s48, 0x100
	s_addc_u32 s49, s49, 0
	s_add_u32 vcc_lo, vcc_lo, 0x100
	s_addc_u32 vcc_hi, vcc_hi, 0
	s_cmp_gt_u32 s57, 13
	s_barrier
	s_cbranch_scc0 .LBB0_170
	v_readlane_b32 s60, v252, 10
	v_readlane_b32 s61, v252, 11
	v_readlane_b32 s68, v255, 14
	v_readlane_b32 s69, v255, 15
	v_readlane_b32 s20, v253, 31
	v_readlane_b32 s21, v253, 32
	v_lshl_add_u32 v210, s2, 8, v231
	v_lshl_or_b32 v213, s34, 8, v233
	v_lshlrev_b32_e32 v208, 12, v210
	v_lshlrev_b32_e32 v209, 11, v210
	v_lshl_add_u32 v208, v213, 2, v208
	v_lshl_add_u32 v209, v213, 1, v209
	global_load_dwordx4 v[128:131], v208, s[60:61]
	global_load_dwordx4 v[132:135], v208, s[60:61] offset:16
	global_load_dwordx4 v[136:139], v208, s[60:61] offset:512
	global_load_dwordx4 v[140:143], v208, s[60:61] offset:528
	s_add_u32 s48, s60, 0x10000
	s_addc_u32 s49, s61, 0
	global_load_dwordx4 v[144:147], v208, s[48:49]
	global_load_dwordx4 v[148:151], v208, s[48:49] offset:16
	global_load_dwordx4 v[152:155], v208, s[48:49] offset:512
	global_load_dwordx4 v[156:159], v208, s[48:49] offset:528
	s_add_u32 s48, s60, 0x20000
	s_addc_u32 s49, s61, 0
	global_load_dwordx4 v[160:163], v208, s[48:49]
	global_load_dwordx4 v[164:167], v208, s[48:49] offset:16
	global_load_dwordx4 v[168:171], v208, s[48:49] offset:512
	global_load_dwordx4 v[172:175], v208, s[48:49] offset:528
	s_add_u32 s48, s60, 0x30000
	s_addc_u32 s49, s61, 0
	global_load_dwordx4 v[236:239], v208, s[48:49]
	global_load_dwordx4 v[240:243], v208, s[48:49] offset:16
	global_load_dwordx4 v[244:247], v208, s[48:49] offset:512
	global_load_dwordx4 v[248:251], v208, s[48:49] offset:528
	v_lshlrev_b32_e32 v210, 6, v210
	v_xor_b32_e32 v211, 16, v225
	v_xor_b32_e32 v212, 32, v225
	v_lshlrev_b32_e32 v211, 2, v211
	v_lshlrev_b32_e32 v212, 2, v212
	s_waitcnt vmcnt(12)
	v_pk_add_f32 v[124:125], v[124:125], v[128:129]
	v_pk_add_f32 v[126:127], v[126:127], v[130:131]
	v_pk_mul_f32 v[214:215], v[124:125], v[124:125]
	v_pk_fma_f32 v[214:215], v[126:127], v[126:127], v[214:215]
	v_pk_add_f32 v[120:121], v[120:121], v[132:133]
	v_pk_add_f32 v[122:123], v[122:123], v[134:135]
	v_pk_fma_f32 v[214:215], v[120:121], v[120:121], v[214:215]
	v_pk_fma_f32 v[214:215], v[122:123], v[122:123], v[214:215]
	v_pk_add_f32 v[116:117], v[116:117], v[136:137]
	v_pk_add_f32 v[118:119], v[118:119], v[138:139]
	v_pk_fma_f32 v[214:215], v[116:117], v[116:117], v[214:215]
	v_pk_fma_f32 v[214:215], v[118:119], v[118:119], v[214:215]
	v_pk_add_f32 v[112:113], v[112:113], v[140:141]
	v_pk_add_f32 v[114:115], v[114:115], v[142:143]
	v_pk_fma_f32 v[214:215], v[112:113], v[112:113], v[214:215]
	v_pk_fma_f32 v[214:215], v[114:115], v[114:115], v[214:215]
	v_cvt_pk_bf16_f32 v128, v124, v125
	v_cvt_pk_bf16_f32 v129, v126, v127
	v_cvt_pk_bf16_f32 v130, v120, v121
	v_cvt_pk_bf16_f32 v131, v122, v123
	v_cvt_pk_bf16_f32 v136, v116, v117
	v_cvt_pk_bf16_f32 v137, v118, v119
	v_cvt_pk_bf16_f32 v138, v112, v113
	v_cvt_pk_bf16_f32 v139, v114, v115
	v_add_f32_e32 v216, v214, v215
	global_store_dwordx4 v209, v[128:131], s[68:69]
	global_store_dwordx4 v209, v[136:139], s[68:69] offset:256
	s_add_u32 s48, s60, 0x80000
	s_addc_u32 s49, s61, 0
	global_load_dwordx4 v[132:135], v208, s[48:49] offset:16
	global_load_dwordx4 v[140:143], v208, s[48:49] offset:528
	global_load_dwordx4 v[128:131], v208, s[48:49]
	global_load_dwordx4 v[136:139], v208, s[48:49] offset:512
	s_waitcnt vmcnt(14)
	v_pk_add_f32 v[108:109], v[108:109], v[144:145]
	v_pk_add_f32 v[110:111], v[110:111], v[146:147]
	v_pk_mul_f32 v[214:215], v[108:109], v[108:109]
	v_pk_fma_f32 v[214:215], v[110:111], v[110:111], v[214:215]
	v_pk_add_f32 v[104:105], v[104:105], v[148:149]
	v_pk_add_f32 v[106:107], v[106:107], v[150:151]
	v_pk_fma_f32 v[214:215], v[104:105], v[104:105], v[214:215]
	v_pk_fma_f32 v[214:215], v[106:107], v[106:107], v[214:215]
	v_pk_add_f32 v[100:101], v[100:101], v[152:153]
	v_pk_add_f32 v[102:103], v[102:103], v[154:155]
	v_pk_fma_f32 v[214:215], v[100:101], v[100:101], v[214:215]
	v_pk_fma_f32 v[214:215], v[102:103], v[102:103], v[214:215]
	v_pk_add_f32 v[96:97], v[96:97], v[156:157]
	v_pk_add_f32 v[98:99], v[98:99], v[158:159]
	v_pk_fma_f32 v[214:215], v[96:97], v[96:97], v[214:215]
	v_pk_fma_f32 v[214:215], v[98:99], v[98:99], v[214:215]
	s_add_u32 s72, s68, 0x8000
	s_addc_u32 s73, s69, 0
	v_cvt_pk_bf16_f32 v144, v108, v109
	v_cvt_pk_bf16_f32 v145, v110, v111
	v_cvt_pk_bf16_f32 v146, v104, v105
	v_cvt_pk_bf16_f32 v147, v106, v107
	v_cvt_pk_bf16_f32 v152, v100, v101
	v_cvt_pk_bf16_f32 v153, v102, v103
	v_cvt_pk_bf16_f32 v154, v96, v97
	v_cvt_pk_bf16_f32 v155, v98, v99
	v_add_f32_e32 v217, v214, v215
	global_store_dwordx4 v209, v[144:147], s[72:73]
	global_store_dwordx4 v209, v[152:155], s[72:73] offset:256
	s_add_u32 s48, s60, 0x90000
	s_addc_u32 s49, s61, 0
	global_load_dwordx4 v[148:151], v208, s[48:49] offset:16
	global_load_dwordx4 v[156:159], v208, s[48:49] offset:528
	global_load_dwordx4 v[144:147], v208, s[48:49]
	global_load_dwordx4 v[152:155], v208, s[48:49] offset:512
	s_waitcnt vmcnt(16)
	v_pk_add_f32 v[92:93], v[92:93], v[160:161]
	v_pk_add_f32 v[94:95], v[94:95], v[162:163]
	v_pk_mul_f32 v[214:215], v[92:93], v[92:93]
	v_pk_fma_f32 v[214:215], v[94:95], v[94:95], v[214:215]
	v_pk_add_f32 v[88:89], v[88:89], v[164:165]
	v_pk_add_f32 v[90:91], v[90:91], v[166:167]
	v_pk_fma_f32 v[214:215], v[88:89], v[88:89], v[214:215]
	v_pk_fma_f32 v[214:215], v[90:91], v[90:91], v[214:215]
	v_pk_add_f32 v[84:85], v[84:85], v[168:169]
	v_pk_add_f32 v[86:87], v[86:87], v[170:171]
	v_pk_fma_f32 v[214:215], v[84:85], v[84:85], v[214:215]
	v_pk_fma_f32 v[214:215], v[86:87], v[86:87], v[214:215]
	v_pk_add_f32 v[80:81], v[80:81], v[172:173]
	v_pk_add_f32 v[82:83], v[82:83], v[174:175]
	v_pk_fma_f32 v[214:215], v[80:81], v[80:81], v[214:215]
	v_pk_fma_f32 v[214:215], v[82:83], v[82:83], v[214:215]
	s_add_u32 s72, s68, 0x10000
	s_addc_u32 s73, s69, 0
	v_cvt_pk_bf16_f32 v160, v92, v93
	v_cvt_pk_bf16_f32 v161, v94, v95
	v_cvt_pk_bf16_f32 v162, v88, v89
	v_cvt_pk_bf16_f32 v163, v90, v91
	v_cvt_pk_bf16_f32 v168, v84, v85
	v_cvt_pk_bf16_f32 v169, v86, v87
	v_cvt_pk_bf16_f32 v170, v80, v81
	v_cvt_pk_bf16_f32 v171, v82, v83
	v_add_f32_e32 v218, v214, v215
	global_store_dwordx4 v209, v[160:163], s[72:73]
	global_store_dwordx4 v209, v[168:171], s[72:73] offset:256
	s_add_u32 s48, s60, 0xa0000
	s_addc_u32 s49, s61, 0
	global_load_dwordx4 v[164:167], v208, s[48:49] offset:16
	global_load_dwordx4 v[172:175], v208, s[48:49] offset:528
	global_load_dwordx4 v[160:163], v208, s[48:49]
	global_load_dwordx4 v[168:171], v208, s[48:49] offset:512
	s_waitcnt vmcnt(18)
	v_pk_add_f32 v[76:77], v[76:77], v[236:237]
	v_pk_add_f32 v[78:79], v[78:79], v[238:239]
	v_pk_mul_f32 v[214:215], v[76:77], v[76:77]
	v_pk_fma_f32 v[214:215], v[78:79], v[78:79], v[214:215]
	v_pk_add_f32 v[72:73], v[72:73], v[240:241]
	v_pk_add_f32 v[74:75], v[74:75], v[242:243]
	v_pk_fma_f32 v[214:215], v[72:73], v[72:73], v[214:215]
	v_pk_fma_f32 v[214:215], v[74:75], v[74:75], v[214:215]
	v_pk_add_f32 v[68:69], v[68:69], v[244:245]
	v_pk_add_f32 v[70:71], v[70:71], v[246:247]
	v_pk_fma_f32 v[214:215], v[68:69], v[68:69], v[214:215]
	v_pk_fma_f32 v[214:215], v[70:71], v[70:71], v[214:215]
	v_pk_add_f32 v[64:65], v[64:65], v[248:249]
	v_pk_add_f32 v[66:67], v[66:67], v[250:251]
	v_pk_fma_f32 v[214:215], v[64:65], v[64:65], v[214:215]
	v_pk_fma_f32 v[214:215], v[66:67], v[66:67], v[214:215]
	s_add_u32 s72, s68, 0x18000
	s_addc_u32 s73, s69, 0
	v_cvt_pk_bf16_f32 v236, v76, v77
	v_cvt_pk_bf16_f32 v237, v78, v79
	v_cvt_pk_bf16_f32 v238, v72, v73
	v_cvt_pk_bf16_f32 v239, v74, v75
	v_cvt_pk_bf16_f32 v244, v68, v69
	v_cvt_pk_bf16_f32 v245, v70, v71
	v_cvt_pk_bf16_f32 v246, v64, v65
	v_cvt_pk_bf16_f32 v247, v66, v67
	v_add_f32_e32 v219, v214, v215
	global_store_dwordx4 v209, v[236:239], s[72:73]
	global_store_dwordx4 v209, v[244:247], s[72:73] offset:256
	s_add_u32 s48, s60, 0xb0000
	s_addc_u32 s49, s61, 0
	global_load_dwordx4 v[240:243], v208, s[48:49] offset:16
	global_load_dwordx4 v[248:251], v208, s[48:49] offset:528
	global_load_dwordx4 v[236:239], v208, s[48:49]
	global_load_dwordx4 v[244:247], v208, s[48:49] offset:512
	s_waitcnt vmcnt(18)
	v_pk_add_f32 v[60:61], v[60:61], v[128:129]
	v_pk_add_f32 v[62:63], v[62:63], v[130:131]
	v_pk_mul_f32 v[214:215], v[60:61], v[60:61]
	v_pk_fma_f32 v[214:215], v[62:63], v[62:63], v[214:215]
	v_pk_add_f32 v[56:57], v[56:57], v[132:133]
	v_pk_add_f32 v[58:59], v[58:59], v[134:135]
	v_pk_fma_f32 v[214:215], v[56:57], v[56:57], v[214:215]
	v_pk_fma_f32 v[214:215], v[58:59], v[58:59], v[214:215]
	v_pk_add_f32 v[52:53], v[52:53], v[136:137]
	v_pk_add_f32 v[54:55], v[54:55], v[138:139]
	v_pk_fma_f32 v[214:215], v[52:53], v[52:53], v[214:215]
	v_pk_fma_f32 v[214:215], v[54:55], v[54:55], v[214:215]
	v_pk_add_f32 v[48:49], v[48:49], v[140:141]
	v_pk_add_f32 v[50:51], v[50:51], v[142:143]
	v_pk_fma_f32 v[214:215], v[48:49], v[48:49], v[214:215]
	v_pk_fma_f32 v[214:215], v[50:51], v[50:51], v[214:215]
	s_add_u32 s72, s68, 0x40000
	s_addc_u32 s73, s69, 0
	v_cvt_pk_bf16_f32 v128, v60, v61
	v_cvt_pk_bf16_f32 v129, v62, v63
	v_cvt_pk_bf16_f32 v130, v56, v57
	v_cvt_pk_bf16_f32 v131, v58, v59
	v_cvt_pk_bf16_f32 v136, v52, v53
	v_cvt_pk_bf16_f32 v137, v54, v55
	v_cvt_pk_bf16_f32 v138, v48, v49
	v_cvt_pk_bf16_f32 v139, v50, v51
	v_add_f32_e32 v184, v214, v215
	global_store_dwordx4 v209, v[128:131], s[72:73]
	global_store_dwordx4 v209, v[136:139], s[72:73] offset:256
	s_waitcnt vmcnt(14)
	v_pk_add_f32 v[44:45], v[44:45], v[144:145]
	v_pk_add_f32 v[46:47], v[46:47], v[146:147]
	v_pk_mul_f32 v[214:215], v[44:45], v[44:45]
	v_pk_fma_f32 v[214:215], v[46:47], v[46:47], v[214:215]
	v_pk_add_f32 v[40:41], v[40:41], v[148:149]
	v_pk_add_f32 v[42:43], v[42:43], v[150:151]
	v_pk_fma_f32 v[214:215], v[40:41], v[40:41], v[214:215]
	v_pk_fma_f32 v[214:215], v[42:43], v[42:43], v[214:215]
	v_pk_add_f32 v[36:37], v[36:37], v[152:153]
	v_pk_add_f32 v[38:39], v[38:39], v[154:155]
	v_pk_fma_f32 v[214:215], v[36:37], v[36:37], v[214:215]
	v_pk_fma_f32 v[214:215], v[38:39], v[38:39], v[214:215]
	v_pk_add_f32 v[32:33], v[32:33], v[156:157]
	v_pk_add_f32 v[34:35], v[34:35], v[158:159]
	v_pk_fma_f32 v[214:215], v[32:33], v[32:33], v[214:215]
	v_pk_fma_f32 v[214:215], v[34:35], v[34:35], v[214:215]
	s_add_u32 s72, s68, 0x48000
	s_addc_u32 s73, s69, 0
	v_cvt_pk_bf16_f32 v144, v44, v45
	v_cvt_pk_bf16_f32 v145, v46, v47
	v_cvt_pk_bf16_f32 v146, v40, v41
	v_cvt_pk_bf16_f32 v147, v42, v43
	v_cvt_pk_bf16_f32 v152, v36, v37
	v_cvt_pk_bf16_f32 v153, v38, v39
	v_cvt_pk_bf16_f32 v154, v32, v33
	v_cvt_pk_bf16_f32 v155, v34, v35
	v_add_f32_e32 v185, v214, v215
	global_store_dwordx4 v209, v[144:147], s[72:73]
	global_store_dwordx4 v209, v[152:155], s[72:73] offset:256
	s_waitcnt vmcnt(10)
	v_pk_add_f32 v[28:29], v[28:29], v[160:161]
	v_pk_add_f32 v[30:31], v[30:31], v[162:163]
	v_pk_mul_f32 v[214:215], v[28:29], v[28:29]
	v_pk_fma_f32 v[214:215], v[30:31], v[30:31], v[214:215]
	v_pk_add_f32 v[24:25], v[24:25], v[164:165]
	v_pk_add_f32 v[26:27], v[26:27], v[166:167]
	v_pk_fma_f32 v[214:215], v[24:25], v[24:25], v[214:215]
	v_pk_fma_f32 v[214:215], v[26:27], v[26:27], v[214:215]
	v_pk_add_f32 v[20:21], v[20:21], v[168:169]
	v_pk_add_f32 v[22:23], v[22:23], v[170:171]
	v_pk_fma_f32 v[214:215], v[20:21], v[20:21], v[214:215]
	v_pk_fma_f32 v[214:215], v[22:23], v[22:23], v[214:215]
	v_pk_add_f32 v[16:17], v[16:17], v[172:173]
	v_pk_add_f32 v[18:19], v[18:19], v[174:175]
	v_pk_fma_f32 v[214:215], v[16:17], v[16:17], v[214:215]
	v_pk_fma_f32 v[214:215], v[18:19], v[18:19], v[214:215]
	s_add_u32 s72, s68, 0x50000
	s_addc_u32 s73, s69, 0
	v_cvt_pk_bf16_f32 v160, v28, v29
	v_cvt_pk_bf16_f32 v161, v30, v31
	v_cvt_pk_bf16_f32 v162, v24, v25
	v_cvt_pk_bf16_f32 v163, v26, v27
	v_cvt_pk_bf16_f32 v168, v20, v21
	v_cvt_pk_bf16_f32 v169, v22, v23
	v_cvt_pk_bf16_f32 v170, v16, v17
	v_cvt_pk_bf16_f32 v171, v18, v19
	v_add_f32_e32 v192, v214, v215
	global_store_dwordx4 v209, v[160:163], s[72:73]
	global_store_dwordx4 v209, v[168:171], s[72:73] offset:256
	s_waitcnt vmcnt(6)
	v_pk_add_f32 v[12:13], v[12:13], v[236:237]
	v_pk_add_f32 v[14:15], v[14:15], v[238:239]
	v_pk_mul_f32 v[214:215], v[12:13], v[12:13]
	v_pk_fma_f32 v[214:215], v[14:15], v[14:15], v[214:215]
	v_pk_add_f32 v[8:9], v[8:9], v[240:241]
	v_pk_add_f32 v[10:11], v[10:11], v[242:243]
	v_pk_fma_f32 v[214:215], v[8:9], v[8:9], v[214:215]
	v_pk_fma_f32 v[214:215], v[10:11], v[10:11], v[214:215]
	v_pk_add_f32 v[4:5], v[4:5], v[244:245]
	v_pk_add_f32 v[6:7], v[6:7], v[246:247]
	v_pk_fma_f32 v[214:215], v[4:5], v[4:5], v[214:215]
	v_pk_fma_f32 v[214:215], v[6:7], v[6:7], v[214:215]
	v_pk_add_f32 v[0:1], v[0:1], v[248:249]
	v_pk_add_f32 v[2:3], v[2:3], v[250:251]
	v_pk_fma_f32 v[214:215], v[0:1], v[0:1], v[214:215]
	v_pk_fma_f32 v[214:215], v[2:3], v[2:3], v[214:215]
	s_add_u32 s72, s68, 0x58000
	s_addc_u32 s73, s69, 0
	v_cvt_pk_bf16_f32 v236, v12, v13
	v_cvt_pk_bf16_f32 v237, v14, v15
	v_cvt_pk_bf16_f32 v238, v8, v9
	v_cvt_pk_bf16_f32 v239, v10, v11
	v_cvt_pk_bf16_f32 v244, v4, v5
	v_cvt_pk_bf16_f32 v245, v6, v7
	v_cvt_pk_bf16_f32 v246, v0, v1
	v_cvt_pk_bf16_f32 v247, v2, v3
	v_add_f32_e32 v235, v214, v215
	global_store_dwordx4 v209, v[236:239], s[72:73]
	global_store_dwordx4 v209, v[244:247], s[72:73] offset:256
	s_nop 0
	ds_bpermute_b32 v128, v211, v216
	ds_bpermute_b32 v129, v211, v217
	ds_bpermute_b32 v130, v211, v218
	ds_bpermute_b32 v131, v211, v219
	ds_bpermute_b32 v132, v211, v184
	ds_bpermute_b32 v133, v211, v185
	ds_bpermute_b32 v134, v211, v192
	ds_bpermute_b32 v135, v211, v235
	s_lshl_b32 s48, s34, 4
	s_lshl_b32 s49, s58, 2
	s_add_i32 s48, s48, s49
	s_add_u32 s72, s20, s48
	s_addc_u32 s73, s21, 0
	s_add_u32 s48, s72, 0x2000
	s_addc_u32 s49, s73, 0
	s_waitcnt lgkmcnt(0)
	v_add_f32_e32 v216, v216, v128
	v_add_f32_e32 v217, v217, v129
	v_add_f32_e32 v218, v218, v130
	v_add_f32_e32 v219, v219, v131
	v_add_f32_e32 v184, v184, v132
	v_add_f32_e32 v185, v185, v133
	v_add_f32_e32 v192, v192, v134
	v_add_f32_e32 v235, v235, v135
	ds_bpermute_b32 v128, v212, v216
	ds_bpermute_b32 v129, v212, v217
	ds_bpermute_b32 v130, v212, v218
	ds_bpermute_b32 v131, v212, v219
	ds_bpermute_b32 v132, v212, v184
	ds_bpermute_b32 v133, v212, v185
	ds_bpermute_b32 v134, v212, v192
	ds_bpermute_b32 v135, v212, v235
	s_waitcnt lgkmcnt(0)
	v_add_f32_e32 v216, v216, v128
	v_add_f32_e32 v217, v217, v129
	v_add_f32_e32 v218, v218, v130
	v_add_f32_e32 v219, v219, v131
	v_add_f32_e32 v184, v184, v132
	v_add_f32_e32 v185, v185, v133
	v_add_f32_e32 v192, v192, v134
	v_add_f32_e32 v235, v235, v135
	s_mov_b64 exec, s[38:39]
	global_store_dword v210, v216, s[72:73]
	global_store_dword v210, v217, s[72:73] offset:1024
	global_store_dword v210, v218, s[72:73] offset:2048
	global_store_dword v210, v219, s[72:73] offset:3072
	global_store_dword v210, v184, s[48:49]
	global_store_dword v210, v185, s[48:49] offset:1024
	global_store_dword v210, v192, s[48:49] offset:2048
	global_store_dword v210, v235, s[48:49] offset:3072
	s_mov_b64 exec, -1
	v_readlane_b32 s64, v255, 6
	v_readlane_b32 s62, v255, 10
	v_readlane_b32 s70, v255, 12
	s_mov_b64 s[74:75], s[92:93]
	v_readlane_b32 s65, v255, 7
	v_readlane_b32 s66, v255, 8
	v_readlane_b32 s67, v255, 9
	v_readlane_b32 s63, v255, 11
	v_readlane_b32 s71, v255, 13
	v_readlane_b32 s72, v252, 22
	v_readlane_b32 s73, v252, 23
	s_lshl_b32 s48, s34, 2
	s_ashr_i32 s49, s48, 31
	s_lshl_b32 s34, s58, 2
	s_mov_b64 s[28:29], -1
	s_branch .LBB0_162
